# attention: rescale compare and QK^T K-address adds moved from the M section head/body to the V section tail (MFMA-only M section)
# baseline (speedup 1.0000x reference)
.LBB0_399:
	v_add_u32_e32 v242, s38, v208
	v_add_u32_e32 v243, s38, v209
	v_add_u32_e32 v244, s38, v210
	v_add_u32_e32 v245, s38, v211
	v_cmp_gt_f32_e32 vcc, 1.0, v215
	s_barrier
	s_cbranch_vccz .LBB0_403
	s_and_saveexec_b64 s[66:67], s[4:5]
	ds_write_b32 v212, v215 offset:128
	s_or_b64 exec, exec, s[66:67]
	s_waitcnt lgkmcnt(0)
	v_add_u32_e32 v146, s73, v207
	ds_read_b128 v[158:161], v146 offset:224
	ds_read_b128 v[154:157], v146 offset:192
	ds_read_b128 v[150:153], v146 offset:160
	ds_read_b128 v[146:149], v146 offset:128
	s_waitcnt lgkmcnt(3)
	v_pk_mul_f32 v[126:127], v[126:127], v[158:159]
	s_waitcnt lgkmcnt(2)
	v_pk_mul_f32 v[122:123], v[122:123], v[154:155]
	s_waitcnt lgkmcnt(1)
	v_pk_mul_f32 v[118:119], v[118:119], v[150:151]
	v_pk_mul_f32 v[128:129], v[128:129], v[160:161]
	v_pk_mul_f32 v[124:125], v[124:125], v[156:157]
	v_pk_mul_f32 v[120:121], v[120:121], v[152:153]
	s_waitcnt lgkmcnt(0)
	v_pk_mul_f32 v[116:117], v[116:117], v[148:149]
	v_pk_mul_f32 v[114:115], v[114:115], v[146:147]
	v_pk_mul_f32 v[110:111], v[110:111], v[158:159]
	v_pk_mul_f32 v[106:107], v[106:107], v[154:155]
	v_pk_mul_f32 v[102:103], v[102:103], v[150:151]
	v_pk_mul_f32 v[112:113], v[112:113], v[160:161]
	v_pk_mul_f32 v[108:109], v[108:109], v[156:157]
	v_pk_mul_f32 v[104:105], v[104:105], v[152:153]
	v_pk_mul_f32 v[100:101], v[100:101], v[148:149]
	v_pk_mul_f32 v[98:99], v[98:99], v[146:147]
	v_pk_mul_f32 v[94:95], v[94:95], v[158:159]
	v_pk_mul_f32 v[90:91], v[90:91], v[154:155]
	v_pk_mul_f32 v[86:87], v[86:87], v[150:151]
	v_pk_mul_f32 v[96:97], v[96:97], v[160:161]
	v_pk_mul_f32 v[92:93], v[92:93], v[156:157]
	v_pk_mul_f32 v[88:89], v[88:89], v[152:153]
	v_pk_mul_f32 v[84:85], v[84:85], v[148:149]
	v_pk_mul_f32 v[82:83], v[82:83], v[146:147]
	v_pk_mul_f32 v[78:79], v[78:79], v[158:159]
	v_pk_mul_f32 v[74:75], v[74:75], v[154:155]
	v_pk_mul_f32 v[70:71], v[70:71], v[150:151]
	v_pk_mul_f32 v[80:81], v[80:81], v[160:161]
	v_pk_mul_f32 v[76:77], v[76:77], v[156:157]
	v_pk_mul_f32 v[72:73], v[72:73], v[152:153]
	v_pk_mul_f32 v[68:69], v[68:69], v[148:149]
	v_pk_mul_f32 v[66:67], v[66:67], v[146:147]
	v_pk_mul_f32 v[62:63], v[62:63], v[158:159]
	v_pk_mul_f32 v[58:59], v[58:59], v[154:155]
	v_pk_mul_f32 v[54:55], v[54:55], v[150:151]
	v_pk_mul_f32 v[64:65], v[64:65], v[160:161]
	v_pk_mul_f32 v[60:61], v[60:61], v[156:157]
	v_pk_mul_f32 v[56:57], v[56:57], v[152:153]
	v_pk_mul_f32 v[52:53], v[52:53], v[148:149]
	v_pk_mul_f32 v[50:51], v[50:51], v[146:147]
	v_pk_mul_f32 v[46:47], v[46:47], v[158:159]
	v_pk_mul_f32 v[42:43], v[42:43], v[154:155]
	v_pk_mul_f32 v[38:39], v[38:39], v[150:151]
	v_pk_mul_f32 v[48:49], v[48:49], v[160:161]
	v_pk_mul_f32 v[44:45], v[44:45], v[156:157]
	v_pk_mul_f32 v[40:41], v[40:41], v[152:153]
	v_pk_mul_f32 v[36:37], v[36:37], v[148:149]
	v_pk_mul_f32 v[34:35], v[34:35], v[146:147]
	v_pk_mul_f32 v[30:31], v[30:31], v[158:159]
	v_pk_mul_f32 v[26:27], v[26:27], v[154:155]
	v_pk_mul_f32 v[22:23], v[22:23], v[150:151]
	v_pk_mul_f32 v[32:33], v[32:33], v[160:161]
	v_pk_mul_f32 v[28:29], v[28:29], v[156:157]
	v_pk_mul_f32 v[24:25], v[24:25], v[152:153]
	v_pk_mul_f32 v[20:21], v[20:21], v[148:149]
	v_pk_mul_f32 v[18:19], v[18:19], v[146:147]
	v_pk_mul_f32 v[14:15], v[14:15], v[158:159]
	v_pk_mul_f32 v[10:11], v[10:11], v[154:155]
	v_pk_mul_f32 v[6:7], v[6:7], v[150:151]
	v_pk_mul_f32 v[16:17], v[16:17], v[160:161]
	v_pk_mul_f32 v[12:13], v[12:13], v[156:157]
	v_pk_mul_f32 v[8:9], v[8:9], v[152:153]
	v_pk_mul_f32 v[4:5], v[4:5], v[148:149]
	v_pk_mul_f32 v[2:3], v[2:3], v[146:147]
.LBB0_403:
	ds_read_b64_tr_b16 v[146:147], v213 offset:0
	ds_read_b64_tr_b16 v[148:149], v213 offset:0x800
	ds_read_b64_tr_b16 v[150:151], v213 offset:0x1000
	ds_read_b64_tr_b16 v[152:153], v213 offset:0x1800
	ds_read_b64_tr_b16 v[154:155], v213 offset:0x2000
	ds_read_b64_tr_b16 v[156:157], v213 offset:0x2800
	ds_read_b64_tr_b16 v[158:159], v213 offset:0x3000
	ds_read_b64_tr_b16 v[160:161], v213 offset:0x3800
	s_waitcnt lgkmcnt(6)
	v_mfma_f32_32x32x16_bf16 v[114:129], v[130:133], v[146:149], v[114:129]
	ds_read_b64_tr_b16 v[218:219], v213 offset:0x200
	ds_read_b64_tr_b16 v[220:221], v213 offset:0xa00
	s_waitcnt lgkmcnt(6)
	v_mfma_f32_32x32x16_bf16 v[114:129], v[134:137], v[150:153], v[114:129]
	ds_read_b64_tr_b16 v[146:147], v213 offset:0x1200
	ds_read_b64_tr_b16 v[148:149], v213 offset:0x1a00
	s_waitcnt lgkmcnt(6)
	v_mfma_f32_32x32x16_bf16 v[114:129], v[138:141], v[154:157], v[114:129]
	ds_read_b64_tr_b16 v[150:151], v213 offset:0x2200
	ds_read_b64_tr_b16 v[152:153], v213 offset:0x2a00
	s_waitcnt lgkmcnt(6)
	v_mfma_f32_32x32x16_bf16 v[114:129], v[142:145], v[158:161], v[114:129]
	ds_read_b64_tr_b16 v[154:155], v213 offset:0x3200
	ds_read_b64_tr_b16 v[156:157], v213 offset:0x3a00
	s_waitcnt lgkmcnt(6)
	v_mfma_f32_32x32x16_bf16 v[98:113], v[130:133], v[218:221], v[98:113]
	ds_read_b64_tr_b16 v[158:159], v213 offset:0x400
	ds_read_b64_tr_b16 v[160:161], v213 offset:0xc00
	s_waitcnt lgkmcnt(6)
	v_mfma_f32_32x32x16_bf16 v[98:113], v[134:137], v[146:149], v[98:113]
	ds_read_b64_tr_b16 v[218:219], v213 offset:0x1400
	ds_read_b64_tr_b16 v[220:221], v213 offset:0x1c00
	s_waitcnt lgkmcnt(6)
	v_mfma_f32_32x32x16_bf16 v[98:113], v[138:141], v[150:153], v[98:113]
	ds_read_b64_tr_b16 v[146:147], v213 offset:0x2400
	ds_read_b64_tr_b16 v[148:149], v213 offset:0x2c00
	s_waitcnt lgkmcnt(6)
	v_mfma_f32_32x32x16_bf16 v[98:113], v[142:145], v[154:157], v[98:113]
	ds_read_b64_tr_b16 v[150:151], v213 offset:0x3400
	ds_read_b64_tr_b16 v[152:153], v213 offset:0x3c00
	s_waitcnt lgkmcnt(6)
	v_mfma_f32_32x32x16_bf16 v[82:97], v[130:133], v[158:161], v[82:97]
	ds_read_b64_tr_b16 v[154:155], v213 offset:0x600
	ds_read_b64_tr_b16 v[156:157], v213 offset:0xe00
	s_waitcnt lgkmcnt(6)
	v_mfma_f32_32x32x16_bf16 v[82:97], v[134:137], v[218:221], v[82:97]
	ds_read_b64_tr_b16 v[158:159], v213 offset:0x1600
	ds_read_b64_tr_b16 v[160:161], v213 offset:0x1e00
	s_waitcnt lgkmcnt(6)
	v_mfma_f32_32x32x16_bf16 v[82:97], v[138:141], v[146:149], v[82:97]
	ds_read_b64_tr_b16 v[218:219], v213 offset:0x2600
	ds_read_b64_tr_b16 v[220:221], v213 offset:0x2e00
	s_waitcnt lgkmcnt(6)
	v_mfma_f32_32x32x16_bf16 v[82:97], v[142:145], v[150:153], v[82:97]
	ds_read_b64_tr_b16 v[146:147], v213 offset:0x3600
	ds_read_b64_tr_b16 v[148:149], v213 offset:0x3e00
	s_waitcnt lgkmcnt(6)
	v_mfma_f32_32x32x16_bf16 v[66:81], v[130:133], v[154:157], v[66:81]
	ds_read_b64_tr_b16 v[150:151], v213 offset:0x4000
	ds_read_b64_tr_b16 v[152:153], v213 offset:0x4800
	s_waitcnt lgkmcnt(6)
	v_mfma_f32_32x32x16_bf16 v[66:81], v[134:137], v[158:161], v[66:81]
	ds_read_b64_tr_b16 v[154:155], v213 offset:0x5000
	ds_read_b64_tr_b16 v[156:157], v213 offset:0x5800
	s_waitcnt lgkmcnt(6)
	v_mfma_f32_32x32x16_bf16 v[66:81], v[138:141], v[218:221], v[66:81]
	ds_read_b64_tr_b16 v[158:159], v213 offset:0x6000
	ds_read_b64_tr_b16 v[160:161], v213 offset:0x6800
	s_waitcnt lgkmcnt(6)
	v_mfma_f32_32x32x16_bf16 v[66:81], v[142:145], v[146:149], v[66:81]
	ds_read_b64_tr_b16 v[218:219], v213 offset:0x7000
	ds_read_b64_tr_b16 v[220:221], v213 offset:0x7800
	s_waitcnt lgkmcnt(6)
	v_mfma_f32_32x32x16_bf16 v[50:65], v[130:133], v[150:153], v[50:65]
	ds_read_b64_tr_b16 v[146:147], v213 offset:0x4200
	ds_read_b64_tr_b16 v[148:149], v213 offset:0x4a00
	s_waitcnt lgkmcnt(6)
	v_mfma_f32_32x32x16_bf16 v[50:65], v[134:137], v[154:157], v[50:65]
	ds_read_b64_tr_b16 v[150:151], v213 offset:0x5200
	ds_read_b64_tr_b16 v[152:153], v213 offset:0x5a00
	s_waitcnt lgkmcnt(6)
	v_mfma_f32_32x32x16_bf16 v[50:65], v[138:141], v[158:161], v[50:65]
	ds_read_b64_tr_b16 v[154:155], v213 offset:0x6200
	ds_read_b64_tr_b16 v[156:157], v213 offset:0x6a00
	s_waitcnt lgkmcnt(6)
	v_mfma_f32_32x32x16_bf16 v[50:65], v[142:145], v[218:221], v[50:65]
	ds_read_b64_tr_b16 v[158:159], v213 offset:0x7200
	ds_read_b64_tr_b16 v[160:161], v213 offset:0x7a00
	s_waitcnt lgkmcnt(6)
	v_mfma_f32_32x32x16_bf16 v[34:49], v[130:133], v[146:149], v[34:49]
	ds_read_b64_tr_b16 v[218:219], v213 offset:0x4400
	ds_read_b64_tr_b16 v[220:221], v213 offset:0x4c00
	s_waitcnt lgkmcnt(6)
	v_mfma_f32_32x32x16_bf16 v[34:49], v[134:137], v[150:153], v[34:49]
	ds_read_b64_tr_b16 v[146:147], v213 offset:0x5400
	ds_read_b64_tr_b16 v[148:149], v213 offset:0x5c00
	s_waitcnt lgkmcnt(6)
	v_mfma_f32_32x32x16_bf16 v[34:49], v[138:141], v[154:157], v[34:49]
	ds_read_b64_tr_b16 v[150:151], v213 offset:0x6400
	ds_read_b64_tr_b16 v[152:153], v213 offset:0x6c00
	s_waitcnt lgkmcnt(6)
	v_mfma_f32_32x32x16_bf16 v[34:49], v[142:145], v[158:161], v[34:49]
	ds_read_b64_tr_b16 v[154:155], v213 offset:0x7400
	ds_read_b64_tr_b16 v[156:157], v213 offset:0x7c00
	s_waitcnt lgkmcnt(6)
	v_mfma_f32_32x32x16_bf16 v[18:33], v[130:133], v[218:221], v[18:33]
	ds_read_b64_tr_b16 v[158:159], v213 offset:0x4600
	ds_read_b64_tr_b16 v[160:161], v213 offset:0x4e00
	s_waitcnt lgkmcnt(6)
	v_mfma_f32_32x32x16_bf16 v[18:33], v[134:137], v[146:149], v[18:33]
	ds_read_b64_tr_b16 v[218:219], v213 offset:0x5600
	ds_read_b64_tr_b16 v[220:221], v213 offset:0x5e00
	s_waitcnt lgkmcnt(6)
	v_mfma_f32_32x32x16_bf16 v[18:33], v[138:141], v[150:153], v[18:33]
	ds_read_b64_tr_b16 v[146:147], v213 offset:0x6600
	ds_read_b64_tr_b16 v[148:149], v213 offset:0x6e00
	s_waitcnt lgkmcnt(6)
	v_mfma_f32_32x32x16_bf16 v[18:33], v[142:145], v[154:157], v[18:33]
	ds_read_b64_tr_b16 v[150:151], v213 offset:0x7600
	ds_read_b64_tr_b16 v[152:153], v213 offset:0x7e00
	s_waitcnt lgkmcnt(6)
	v_mfma_f32_32x32x16_bf16 v[2:17], v[130:133], v[158:161], v[2:17]
	s_waitcnt lgkmcnt(4)
	v_mfma_f32_32x32x16_bf16 v[2:17], v[134:137], v[218:221], v[2:17]
	s_waitcnt lgkmcnt(2)
	v_mfma_f32_32x32x16_bf16 v[2:17], v[138:141], v[146:149], v[2:17]
	s_waitcnt lgkmcnt(0)
	v_mfma_f32_32x32x16_bf16 v[2:17], v[142:145], v[150:153], v[2:17]
	ds_read_b128 v[130:133], v242 offset:0
	ds_read_b128 v[134:137], v242 offset:0x2000
	ds_read_b128 v[218:221], v243 offset:0
	ds_read_b128 v[222:225], v243 offset:0x2000
	ds_read_b128 v[226:229], v244 offset:0
	ds_read_b128 v[230:233], v244 offset:0x2000
	s_waitcnt lgkmcnt(4)
	v_mfma_f32_32x32x16_bf16 v[146:161], v[130:133], v[162:165], 0
	v_mfma_f32_32x32x16_bf16 v[130:145], v[134:137], v[162:165], 0
	ds_read_b128 v[234:237], v245 offset:0
	ds_read_b128 v[238:241], v245 offset:0x2000
	s_waitcnt lgkmcnt(4)
	v_mfma_f32_32x32x16_bf16 v[146:161], v[218:221], v[166:169], v[146:161]
	v_mfma_f32_32x32x16_bf16 v[130:145], v[222:225], v[166:169], v[130:145]
	ds_read_b128 v[218:221], v242 offset:0x80
	ds_read_b128 v[222:225], v242 offset:0x2080
	s_waitcnt lgkmcnt(4)
	v_mfma_f32_32x32x16_bf16 v[146:161], v[226:229], v[170:173], v[146:161]
	v_mfma_f32_32x32x16_bf16 v[130:145], v[230:233], v[170:173], v[130:145]
	ds_read_b128 v[226:229], v243 offset:0x80
	ds_read_b128 v[230:233], v243 offset:0x2080
	s_waitcnt lgkmcnt(4)
	v_mfma_f32_32x32x16_bf16 v[146:161], v[234:237], v[174:177], v[146:161]
	v_mfma_f32_32x32x16_bf16 v[130:145], v[238:241], v[174:177], v[130:145]
	ds_read_b128 v[234:237], v244 offset:0x80
	ds_read_b128 v[238:241], v244 offset:0x2080
	s_waitcnt lgkmcnt(4)
	v_mfma_f32_32x32x16_bf16 v[146:161], v[218:221], v[178:181], v[146:161]
	v_mfma_f32_32x32x16_bf16 v[130:145], v[222:225], v[178:181], v[130:145]
	ds_read_b128 v[218:221], v245 offset:0x80
	ds_read_b128 v[222:225], v245 offset:0x2080
	s_waitcnt lgkmcnt(4)
	v_mfma_f32_32x32x16_bf16 v[146:161], v[226:229], v[182:185], v[146:161]
	v_mfma_f32_32x32x16_bf16 v[130:145], v[230:233], v[182:185], v[130:145]
	s_waitcnt lgkmcnt(2)
	v_mfma_f32_32x32x16_bf16 v[146:161], v[234:237], v[186:189], v[146:161]
	v_mfma_f32_32x32x16_bf16 v[130:145], v[238:241], v[186:189], v[130:145]
	s_waitcnt lgkmcnt(0)
	v_mfma_f32_32x32x16_bf16 v[146:161], v[218:221], v[190:193], v[146:161]
	s_and_b64 vcc, exec, s[6:7]
	v_mfma_f32_32x32x16_bf16 v[130:145], v[222:225], v[190:193], v[130:145]
	s_cbranch_vccnz .LBB0_405
	s_waitcnt vmcnt(0)

.LBB0_419:
	v_add_u32_e32 v221, s38, v208
	v_add_u32_e32 v246, s38, v209
	v_add_u32_e32 v247, s38, v210
	v_add_u32_e32 v248, s38, v211
	v_cmp_gt_f32_e32 vcc, 1.0, v218
	s_barrier
	s_cbranch_vccz .LBB0_423
	s_and_saveexec_b64 s[8:9], s[4:5]
	ds_write_b32 v212, v218 offset:128
	s_or_b64 exec, exec, s[8:9]
	s_waitcnt lgkmcnt(0)
	v_add_u32_e32 v146, s73, v207
	ds_read_b128 v[158:161], v146 offset:224
	ds_read_b128 v[154:157], v146 offset:192
	ds_read_b128 v[150:153], v146 offset:160
	ds_read_b128 v[146:149], v146 offset:128
	s_waitcnt lgkmcnt(3)
	v_pk_mul_f32 v[126:127], v[126:127], v[158:159]
	s_waitcnt lgkmcnt(2)
	v_pk_mul_f32 v[122:123], v[122:123], v[154:155]
	s_waitcnt lgkmcnt(1)
	v_pk_mul_f32 v[118:119], v[118:119], v[150:151]
	v_pk_mul_f32 v[128:129], v[128:129], v[160:161]
	v_pk_mul_f32 v[124:125], v[124:125], v[156:157]
	v_pk_mul_f32 v[120:121], v[120:121], v[152:153]
	s_waitcnt lgkmcnt(0)
	v_pk_mul_f32 v[116:117], v[116:117], v[148:149]
	v_pk_mul_f32 v[114:115], v[114:115], v[146:147]
	v_pk_mul_f32 v[110:111], v[110:111], v[158:159]
	v_pk_mul_f32 v[106:107], v[106:107], v[154:155]
	v_pk_mul_f32 v[102:103], v[102:103], v[150:151]
	v_pk_mul_f32 v[112:113], v[112:113], v[160:161]
	v_pk_mul_f32 v[108:109], v[108:109], v[156:157]
	v_pk_mul_f32 v[104:105], v[104:105], v[152:153]
	v_pk_mul_f32 v[100:101], v[100:101], v[148:149]
	v_pk_mul_f32 v[98:99], v[98:99], v[146:147]
	v_pk_mul_f32 v[94:95], v[94:95], v[158:159]
	v_pk_mul_f32 v[90:91], v[90:91], v[154:155]
	v_pk_mul_f32 v[86:87], v[86:87], v[150:151]
	v_pk_mul_f32 v[96:97], v[96:97], v[160:161]
	v_pk_mul_f32 v[92:93], v[92:93], v[156:157]
	v_pk_mul_f32 v[88:89], v[88:89], v[152:153]
	v_pk_mul_f32 v[84:85], v[84:85], v[148:149]
	v_pk_mul_f32 v[82:83], v[82:83], v[146:147]
	v_pk_mul_f32 v[78:79], v[78:79], v[158:159]
	v_pk_mul_f32 v[74:75], v[74:75], v[154:155]
	v_pk_mul_f32 v[70:71], v[70:71], v[150:151]
	v_pk_mul_f32 v[80:81], v[80:81], v[160:161]
	v_pk_mul_f32 v[76:77], v[76:77], v[156:157]
	v_pk_mul_f32 v[72:73], v[72:73], v[152:153]
	v_pk_mul_f32 v[68:69], v[68:69], v[148:149]
	v_pk_mul_f32 v[66:67], v[66:67], v[146:147]
	v_pk_mul_f32 v[62:63], v[62:63], v[158:159]
	v_pk_mul_f32 v[58:59], v[58:59], v[154:155]
	v_pk_mul_f32 v[54:55], v[54:55], v[150:151]
	v_pk_mul_f32 v[64:65], v[64:65], v[160:161]
	v_pk_mul_f32 v[60:61], v[60:61], v[156:157]
	v_pk_mul_f32 v[56:57], v[56:57], v[152:153]
	v_pk_mul_f32 v[52:53], v[52:53], v[148:149]
	v_pk_mul_f32 v[50:51], v[50:51], v[146:147]
	v_pk_mul_f32 v[46:47], v[46:47], v[158:159]
	v_pk_mul_f32 v[42:43], v[42:43], v[154:155]
	v_pk_mul_f32 v[38:39], v[38:39], v[150:151]
	v_pk_mul_f32 v[48:49], v[48:49], v[160:161]
	v_pk_mul_f32 v[44:45], v[44:45], v[156:157]
	v_pk_mul_f32 v[40:41], v[40:41], v[152:153]
	v_pk_mul_f32 v[36:37], v[36:37], v[148:149]
	v_pk_mul_f32 v[34:35], v[34:35], v[146:147]
	v_pk_mul_f32 v[30:31], v[30:31], v[158:159]
	v_pk_mul_f32 v[26:27], v[26:27], v[154:155]
	v_pk_mul_f32 v[22:23], v[22:23], v[150:151]
	v_pk_mul_f32 v[32:33], v[32:33], v[160:161]
	v_pk_mul_f32 v[28:29], v[28:29], v[156:157]
	v_pk_mul_f32 v[24:25], v[24:25], v[152:153]
	v_pk_mul_f32 v[20:21], v[20:21], v[148:149]
	v_pk_mul_f32 v[18:19], v[18:19], v[146:147]
	v_pk_mul_f32 v[14:15], v[14:15], v[158:159]
	v_pk_mul_f32 v[10:11], v[10:11], v[154:155]
	v_pk_mul_f32 v[6:7], v[6:7], v[150:151]
	v_pk_mul_f32 v[16:17], v[16:17], v[160:161]
	v_pk_mul_f32 v[12:13], v[12:13], v[156:157]
	v_pk_mul_f32 v[8:9], v[8:9], v[152:153]
	v_pk_mul_f32 v[4:5], v[4:5], v[148:149]
	v_pk_mul_f32 v[2:3], v[2:3], v[146:147]
.LBB0_423:
	ds_read_b64_tr_b16 v[146:147], v214 offset:0
	ds_read_b64_tr_b16 v[148:149], v214 offset:0x800
	ds_read_b64_tr_b16 v[150:151], v214 offset:0x1000
	ds_read_b64_tr_b16 v[152:153], v214 offset:0x1800
	ds_read_b64_tr_b16 v[154:155], v214 offset:0x2000
	ds_read_b64_tr_b16 v[156:157], v214 offset:0x2800
	ds_read_b64_tr_b16 v[158:159], v214 offset:0x3000
	ds_read_b64_tr_b16 v[160:161], v214 offset:0x3800
	s_waitcnt lgkmcnt(6)
	v_mfma_f32_32x32x16_bf16 v[114:129], v[130:133], v[146:149], v[114:129]
	ds_read_b64_tr_b16 v[222:223], v214 offset:0x200
	ds_read_b64_tr_b16 v[224:225], v214 offset:0xa00
	s_waitcnt lgkmcnt(6)
	v_mfma_f32_32x32x16_bf16 v[114:129], v[134:137], v[150:153], v[114:129]
	ds_read_b64_tr_b16 v[146:147], v214 offset:0x1200
	ds_read_b64_tr_b16 v[148:149], v214 offset:0x1a00
	s_waitcnt lgkmcnt(6)
	v_mfma_f32_32x32x16_bf16 v[114:129], v[138:141], v[154:157], v[114:129]
	ds_read_b64_tr_b16 v[150:151], v214 offset:0x2200
	ds_read_b64_tr_b16 v[152:153], v214 offset:0x2a00
	s_waitcnt lgkmcnt(6)
	v_mfma_f32_32x32x16_bf16 v[114:129], v[142:145], v[158:161], v[114:129]
	ds_read_b64_tr_b16 v[154:155], v214 offset:0x3200
	ds_read_b64_tr_b16 v[156:157], v214 offset:0x3a00
	s_waitcnt lgkmcnt(6)
	v_mfma_f32_32x32x16_bf16 v[98:113], v[130:133], v[222:225], v[98:113]
	ds_read_b64_tr_b16 v[158:159], v214 offset:0x400
	ds_read_b64_tr_b16 v[160:161], v214 offset:0xc00
	s_waitcnt lgkmcnt(6)
	v_mfma_f32_32x32x16_bf16 v[98:113], v[134:137], v[146:149], v[98:113]
	ds_read_b64_tr_b16 v[222:223], v214 offset:0x1400
	ds_read_b64_tr_b16 v[224:225], v214 offset:0x1c00
	s_waitcnt lgkmcnt(6)
	v_mfma_f32_32x32x16_bf16 v[98:113], v[138:141], v[150:153], v[98:113]
	ds_read_b64_tr_b16 v[146:147], v214 offset:0x2400
	ds_read_b64_tr_b16 v[148:149], v214 offset:0x2c00
	s_waitcnt lgkmcnt(6)
	v_mfma_f32_32x32x16_bf16 v[98:113], v[142:145], v[154:157], v[98:113]
	ds_read_b64_tr_b16 v[150:151], v214 offset:0x3400
	ds_read_b64_tr_b16 v[152:153], v214 offset:0x3c00
	s_waitcnt lgkmcnt(6)
	v_mfma_f32_32x32x16_bf16 v[82:97], v[130:133], v[158:161], v[82:97]
	ds_read_b64_tr_b16 v[154:155], v214 offset:0x600
	ds_read_b64_tr_b16 v[156:157], v214 offset:0xe00
	s_waitcnt lgkmcnt(6)
	v_mfma_f32_32x32x16_bf16 v[82:97], v[134:137], v[222:225], v[82:97]
	ds_read_b64_tr_b16 v[158:159], v214 offset:0x1600
	ds_read_b64_tr_b16 v[160:161], v214 offset:0x1e00
	s_waitcnt lgkmcnt(6)
	v_mfma_f32_32x32x16_bf16 v[82:97], v[138:141], v[146:149], v[82:97]
	ds_read_b64_tr_b16 v[222:223], v214 offset:0x2600
	ds_read_b64_tr_b16 v[224:225], v214 offset:0x2e00
	s_waitcnt lgkmcnt(6)
	v_mfma_f32_32x32x16_bf16 v[82:97], v[142:145], v[150:153], v[82:97]
	ds_read_b64_tr_b16 v[146:147], v214 offset:0x3600
	ds_read_b64_tr_b16 v[148:149], v214 offset:0x3e00
	s_waitcnt lgkmcnt(6)
	v_mfma_f32_32x32x16_bf16 v[66:81], v[130:133], v[154:157], v[66:81]
	ds_read_b64_tr_b16 v[150:151], v214 offset:0x4000
	ds_read_b64_tr_b16 v[152:153], v214 offset:0x4800
	s_waitcnt lgkmcnt(6)
	v_mfma_f32_32x32x16_bf16 v[66:81], v[134:137], v[158:161], v[66:81]
	ds_read_b64_tr_b16 v[154:155], v214 offset:0x5000
	ds_read_b64_tr_b16 v[156:157], v214 offset:0x5800
	s_waitcnt lgkmcnt(6)
	v_mfma_f32_32x32x16_bf16 v[66:81], v[138:141], v[222:225], v[66:81]
	ds_read_b64_tr_b16 v[158:159], v214 offset:0x6000
	ds_read_b64_tr_b16 v[160:161], v214 offset:0x6800
	s_waitcnt lgkmcnt(6)
	v_mfma_f32_32x32x16_bf16 v[66:81], v[142:145], v[146:149], v[66:81]
	ds_read_b64_tr_b16 v[222:223], v214 offset:0x7000
	ds_read_b64_tr_b16 v[224:225], v214 offset:0x7800
	s_waitcnt lgkmcnt(6)
	v_mfma_f32_32x32x16_bf16 v[50:65], v[130:133], v[150:153], v[50:65]
	ds_read_b64_tr_b16 v[146:147], v214 offset:0x4200
	ds_read_b64_tr_b16 v[148:149], v214 offset:0x4a00
	s_waitcnt lgkmcnt(6)
	v_mfma_f32_32x32x16_bf16 v[50:65], v[134:137], v[154:157], v[50:65]
	ds_read_b64_tr_b16 v[150:151], v214 offset:0x5200
	ds_read_b64_tr_b16 v[152:153], v214 offset:0x5a00
	s_waitcnt lgkmcnt(6)
	v_mfma_f32_32x32x16_bf16 v[50:65], v[138:141], v[158:161], v[50:65]
	ds_read_b64_tr_b16 v[154:155], v214 offset:0x6200
	ds_read_b64_tr_b16 v[156:157], v214 offset:0x6a00
	s_waitcnt lgkmcnt(6)
	v_mfma_f32_32x32x16_bf16 v[50:65], v[142:145], v[222:225], v[50:65]
	ds_read_b64_tr_b16 v[158:159], v214 offset:0x7200
	ds_read_b64_tr_b16 v[160:161], v214 offset:0x7a00
	s_waitcnt lgkmcnt(6)
	v_mfma_f32_32x32x16_bf16 v[34:49], v[130:133], v[146:149], v[34:49]
	ds_read_b64_tr_b16 v[222:223], v214 offset:0x4400
	ds_read_b64_tr_b16 v[224:225], v214 offset:0x4c00
	s_waitcnt lgkmcnt(6)
	v_mfma_f32_32x32x16_bf16 v[34:49], v[134:137], v[150:153], v[34:49]
	ds_read_b64_tr_b16 v[146:147], v214 offset:0x5400
	ds_read_b64_tr_b16 v[148:149], v214 offset:0x5c00
	s_waitcnt lgkmcnt(6)
	v_mfma_f32_32x32x16_bf16 v[34:49], v[138:141], v[154:157], v[34:49]
	ds_read_b64_tr_b16 v[150:151], v214 offset:0x6400
	ds_read_b64_tr_b16 v[152:153], v214 offset:0x6c00
	s_waitcnt lgkmcnt(6)
	v_mfma_f32_32x32x16_bf16 v[34:49], v[142:145], v[158:161], v[34:49]
	ds_read_b64_tr_b16 v[154:155], v214 offset:0x7400
	ds_read_b64_tr_b16 v[156:157], v214 offset:0x7c00
	s_waitcnt lgkmcnt(6)
	v_mfma_f32_32x32x16_bf16 v[18:33], v[130:133], v[222:225], v[18:33]
	ds_read_b64_tr_b16 v[158:159], v214 offset:0x4600
	ds_read_b64_tr_b16 v[160:161], v214 offset:0x4e00
	s_waitcnt lgkmcnt(6)
	v_mfma_f32_32x32x16_bf16 v[18:33], v[134:137], v[146:149], v[18:33]
	ds_read_b64_tr_b16 v[222:223], v214 offset:0x5600
	ds_read_b64_tr_b16 v[224:225], v214 offset:0x5e00
	s_waitcnt lgkmcnt(6)
	v_mfma_f32_32x32x16_bf16 v[18:33], v[138:141], v[150:153], v[18:33]
	ds_read_b64_tr_b16 v[146:147], v214 offset:0x6600
	ds_read_b64_tr_b16 v[148:149], v214 offset:0x6e00
	s_waitcnt lgkmcnt(6)
	v_mfma_f32_32x32x16_bf16 v[18:33], v[142:145], v[154:157], v[18:33]
	ds_read_b64_tr_b16 v[150:151], v214 offset:0x7600
	ds_read_b64_tr_b16 v[152:153], v214 offset:0x7e00
	s_waitcnt lgkmcnt(6)
	v_mfma_f32_32x32x16_bf16 v[2:17], v[130:133], v[158:161], v[2:17]
	s_waitcnt lgkmcnt(4)
	v_mfma_f32_32x32x16_bf16 v[2:17], v[134:137], v[222:225], v[2:17]
	s_waitcnt lgkmcnt(2)
	v_mfma_f32_32x32x16_bf16 v[2:17], v[138:141], v[146:149], v[2:17]
	s_waitcnt lgkmcnt(0)
	v_mfma_f32_32x32x16_bf16 v[2:17], v[142:145], v[150:153], v[2:17]
	ds_read_b128 v[130:133], v221 offset:0
	ds_read_b128 v[134:137], v221 offset:0x2000
	ds_read_b128 v[222:225], v246 offset:0
	ds_read_b128 v[226:229], v246 offset:0x2000
	ds_read_b128 v[230:233], v247 offset:0
	ds_read_b128 v[234:237], v247 offset:0x2000
	s_waitcnt lgkmcnt(4)
	v_mfma_f32_32x32x16_bf16 v[146:161], v[130:133], v[162:165], 0
	v_mfma_f32_32x32x16_bf16 v[130:145], v[134:137], v[162:165], 0
	ds_read_b128 v[238:241], v248 offset:0
	ds_read_b128 v[242:245], v248 offset:0x2000
	s_waitcnt lgkmcnt(4)
	v_mfma_f32_32x32x16_bf16 v[146:161], v[222:225], v[166:169], v[146:161]
	v_mfma_f32_32x32x16_bf16 v[130:145], v[226:229], v[166:169], v[130:145]
	ds_read_b128 v[222:225], v221 offset:0x80
	ds_read_b128 v[226:229], v221 offset:0x2080
	s_waitcnt lgkmcnt(4)
	v_mfma_f32_32x32x16_bf16 v[146:161], v[230:233], v[170:173], v[146:161]
	v_mfma_f32_32x32x16_bf16 v[130:145], v[234:237], v[170:173], v[130:145]
	ds_read_b128 v[230:233], v246 offset:0x80
	ds_read_b128 v[234:237], v246 offset:0x2080
	s_waitcnt lgkmcnt(4)
	v_mfma_f32_32x32x16_bf16 v[146:161], v[238:241], v[174:177], v[146:161]
	v_mfma_f32_32x32x16_bf16 v[130:145], v[242:245], v[174:177], v[130:145]
	ds_read_b128 v[238:241], v247 offset:0x80
	ds_read_b128 v[242:245], v247 offset:0x2080
	s_waitcnt lgkmcnt(4)
	v_mfma_f32_32x32x16_bf16 v[146:161], v[222:225], v[178:181], v[146:161]
	v_mfma_f32_32x32x16_bf16 v[130:145], v[226:229], v[178:181], v[130:145]
	ds_read_b128 v[222:225], v248 offset:0x80
	ds_read_b128 v[226:229], v248 offset:0x2080
	s_waitcnt lgkmcnt(4)
	v_mfma_f32_32x32x16_bf16 v[146:161], v[230:233], v[182:185], v[146:161]
	v_mfma_f32_32x32x16_bf16 v[130:145], v[234:237], v[182:185], v[130:145]
	s_waitcnt lgkmcnt(2)
	v_mfma_f32_32x32x16_bf16 v[146:161], v[238:241], v[186:189], v[146:161]
	v_mfma_f32_32x32x16_bf16 v[130:145], v[242:245], v[186:189], v[130:145]
	s_waitcnt lgkmcnt(0)
	v_mfma_f32_32x32x16_bf16 v[146:161], v[222:225], v[190:193], v[146:161]
	s_and_b64 vcc, exec, s[6:7]
	v_mfma_f32_32x32x16_bf16 v[130:145], v[226:229], v[190:193], v[130:145]
	s_cbranch_vccnz .LBB0_425
	s_waitcnt vmcnt(0)
